# k16 + L0 q/k projection plain-path epilogue (stick-breaking q,k tiles) with row rstd*qscale from an LDS table (v_rsq) instead of per-lane 32 loads + 8 sqrt/div
# baseline (speedup 1.0000x reference)
; __device__ __forceinline__ unsigned cvtpk(float lo, float hi) { f32x2_t v = {lo, hi}; bf16x2_t b = __builtin_convertvector(v, bf16x2_t); return __builtin_bit_cast(unsigned, b); }
; __device__ __forceinline__ float ssq_sum(const float* p) {
;     const f32x4 a = *(const f32x4*)p, b = *(const f32x4*)(p + 4), c = *(const f32x4*)(p + 8), d = *(const f32x4*)(p + 12);
;     return (((a[0] + a[1]) + (a[2] + a[3])) + ((b[0] + b[1]) + (b[2] + b[3]))) + (((c[0] + c[1]) + (c[2] + c[3])) + ((d[0] + d[1]) + (d[2] + d[3])));
;     __device__ __forceinline__ void operator()(const f32x4 (&acc)[2][2][4][2], const Unit& u, int wr, int wc, int fr, int fq) const {
;     ...
;         if (u.pn >= 4) {
;             const int col0 = u.pn * BM + wc * 32 + 8 * fq;
; #pragma unroll
;             for (int ai = 0; ai < 2; ++ai)
; #pragma unroll
;                 for (int m = 0; m < 4; ++m) {
;                     const int row = row0 + ai * HALF + m * 16;
;                     const float rs = (u.pn < 6 ? qscale : 1.0f) / sqrtf(ssq_sum(ssq_in + (size_t)row * 16) * (1.0f / DM) + EPS);
; #pragma unroll
;                     for (int bj = 0; bj < 2; ++bj) {
;                         const f32x4 v0 = acc[ai][bj][m][0] * rs, v1 = acc[ai][bj][m][1] * rs;
;                         u32x4 w; w.x = cvtpk(v0[0], v0[1]); w.y = cvtpk(v0[2], v0[3]); w.z = cvtpk(v1[0], v1[1]); w.w = cvtpk(v1[2], v1[3]);
;                         *(u32x4*)(O + (size_t)row * 2048 + col0 + bj * HALF) = w;
;                     }
;                 }
;             return;
.LBB0_479:
	s_sub_u32 s1, s0, s54
	v_readlane_b32 vcc_lo, v254, 7
	v_mbcnt_lo_u32_b32 v128, -1, 0
	v_mbcnt_hi_u32_b32 v128, -1, v128
	v_lshrrev_b32_e32 v129, 1, v128
	v_lshl_add_u32 v129, vcc_lo, 5, v129
	v_and_b32_e32 v130, 1, v128
	v_add_u32_e32 v131, s1, v129
	v_lshlrev_b32_e32 v131, 6, v131
	v_lshl_add_u32 v131, v130, 5, v131
	global_load_dwordx4 v[132:135], v131, s[18:19]
	global_load_dwordx4 v[136:139], v131, s[18:19] offset:16
	s_lshl_b32 s0, s66, 8
	s_or_b32 s0, s0, s55
	s_cmp_lt_u32 s66, 6
	s_cselect_b64 s[8:9], -1, 0
	v_lshl_add_u32 v141, v206, 3, s0
	v_lshlrev_b32_e32 v140, 12, v168
	v_lshl_add_u32 v140, v141, 1, v140
	v_cndmask_b32_e64 v141, 1.0, v205, s[8:9]
	v_lshlrev_b32_e32 v129, 2, v129
	v_add_u32_e32 v129, 0x20100, v129
	v_and_b32_e32 v130, 0xff, v168
	v_lshlrev_b32_e32 v130, 2, v130
	v_add_u32_e32 v130, 0x20100, v130
	s_waitcnt vmcnt(0)
	v_pk_add_f32 v[132:133], v[132:133], v[134:135]
	v_pk_add_f32 v[136:137], v[136:137], v[138:139]
	v_pk_add_f32 v[132:133], v[132:133], v[136:137]
	v_add_f32_e32 v132, v132, v133
	s_nop 1
	v_add_f32_dpp v132, v132, v132 quad_perm:[1,0,3,2] row_mask:0xf bank_mask:0xf
	v_fmamk_f32 v132, v132, 0x3a800000, v202
	v_rsq_f32_e32 v132, v132
	s_nop 0
	v_mul_f32_e32 v132, v132, v141
	ds_write_b32 v129, v132
	s_waitcnt lgkmcnt(0)
	s_barrier
	ds_read_b32 v142, v130 offset:0
	ds_read_b32 v143, v130 offset:64
	ds_read_b32 v144, v130 offset:128
	ds_read_b32 v145, v130 offset:192
	ds_read_b32 v146, v130 offset:512
	ds_read_b32 v147, v130 offset:576
	ds_read_b32 v148, v130 offset:640
	ds_read_b32 v149, v130 offset:704
	s_waitcnt lgkmcnt(7)
	v_mul_f32_e32 v124, v142, v124
	v_mul_f32_e32 v125, v142, v125
	v_mul_f32_e32 v126, v142, v126
	v_mul_f32_e32 v127, v142, v127
	v_mul_f32_e32 v120, v142, v120
	v_mul_f32_e32 v121, v142, v121
	v_mul_f32_e32 v122, v142, v122
	v_mul_f32_e32 v123, v142, v123
	v_mul_f32_e32 v116, v142, v116
	v_mul_f32_e32 v117, v142, v117
	v_mul_f32_e32 v118, v142, v118
	v_mul_f32_e32 v119, v142, v119
	v_mul_f32_e32 v112, v142, v112
	v_mul_f32_e32 v113, v142, v113
	v_mul_f32_e32 v114, v142, v114
	v_mul_f32_e32 v115, v142, v115
	v_cvt_pk_bf16_f32 v124, v124, v125
	v_cvt_pk_bf16_f32 v125, v126, v127
	v_cvt_pk_bf16_f32 v126, v120, v121
	v_cvt_pk_bf16_f32 v127, v122, v123
	v_cvt_pk_bf16_f32 v116, v116, v117
	v_cvt_pk_bf16_f32 v117, v118, v119
	v_cvt_pk_bf16_f32 v118, v112, v113
	v_cvt_pk_bf16_f32 v119, v114, v115
	global_store_dwordx4 v140, v[124:127], s[22:23]
	global_store_dwordx4 v140, v[116:119], s[22:23] offset:256
	s_waitcnt lgkmcnt(6)
	v_mul_f32_e32 v108, v143, v108
	v_mul_f32_e32 v109, v143, v109
	v_mul_f32_e32 v110, v143, v110
	v_mul_f32_e32 v111, v143, v111
	v_mul_f32_e32 v104, v143, v104
	v_mul_f32_e32 v105, v143, v105
	v_mul_f32_e32 v106, v143, v106
	v_mul_f32_e32 v107, v143, v107
	v_mul_f32_e32 v100, v143, v100
	v_mul_f32_e32 v101, v143, v101
	v_mul_f32_e32 v102, v143, v102
	v_mul_f32_e32 v103, v143, v103
	v_mul_f32_e32 v96, v143, v96
	v_mul_f32_e32 v97, v143, v97
	v_mul_f32_e32 v98, v143, v98
	v_mul_f32_e32 v99, v143, v99
	v_cvt_pk_bf16_f32 v108, v108, v109
	v_cvt_pk_bf16_f32 v109, v110, v111
	v_cvt_pk_bf16_f32 v110, v104, v105
	v_cvt_pk_bf16_f32 v111, v106, v107
	v_cvt_pk_bf16_f32 v100, v100, v101
	v_cvt_pk_bf16_f32 v101, v102, v103
	v_cvt_pk_bf16_f32 v102, v96, v97
	v_cvt_pk_bf16_f32 v103, v98, v99
	v_add_u32_e32 v141, 0x10000, v140
	global_store_dwordx4 v141, v[108:111], s[22:23]
	global_store_dwordx4 v141, v[100:103], s[22:23] offset:256
	s_waitcnt lgkmcnt(5)
	v_mul_f32_e32 v92, v144, v92
	v_mul_f32_e32 v93, v144, v93
	v_mul_f32_e32 v94, v144, v94
	v_mul_f32_e32 v95, v144, v95
	v_mul_f32_e32 v88, v144, v88
	v_mul_f32_e32 v89, v144, v89
	v_mul_f32_e32 v90, v144, v90
	v_mul_f32_e32 v91, v144, v91
	v_mul_f32_e32 v84, v144, v84
	v_mul_f32_e32 v85, v144, v85
	v_mul_f32_e32 v86, v144, v86
	v_mul_f32_e32 v87, v144, v87
	v_mul_f32_e32 v80, v144, v80
	v_mul_f32_e32 v81, v144, v81
	v_mul_f32_e32 v82, v144, v82
	v_mul_f32_e32 v83, v144, v83
	v_cvt_pk_bf16_f32 v92, v92, v93
	v_cvt_pk_bf16_f32 v93, v94, v95
	v_cvt_pk_bf16_f32 v94, v88, v89
	v_cvt_pk_bf16_f32 v95, v90, v91
	v_cvt_pk_bf16_f32 v84, v84, v85
	v_cvt_pk_bf16_f32 v85, v86, v87
	v_cvt_pk_bf16_f32 v86, v80, v81
	v_cvt_pk_bf16_f32 v87, v82, v83
	v_add_u32_e32 v141, 0x20000, v140
	global_store_dwordx4 v141, v[92:95], s[22:23]
	global_store_dwordx4 v141, v[84:87], s[22:23] offset:256
	s_waitcnt lgkmcnt(4)
; __device__ __forceinline__ unsigned cvtpk(float lo, float hi) { f32x2_t v = {lo, hi}; bf16x2_t b = __builtin_convertvector(v, bf16x2_t); return __builtin_bit_cast(unsigned, b); }
;     __device__ __forceinline__ void operator()(const f32x4 (&acc)[2][2][4][2], const Unit& u, int wr, int wc, int fr, int fq) const {
;     ...
;         if (u.pn >= 4) {
;             const int col0 = u.pn * BM + wc * 32 + 8 * fq;
; #pragma unroll
;             for (int ai = 0; ai < 2; ++ai)
; #pragma unroll
;                 for (int m = 0; m < 4; ++m) {
;                     const int row = row0 + ai * HALF + m * 16;
;                     const float rs = (u.pn < 6 ? qscale : 1.0f) / sqrtf(ssq_sum(ssq_in + (size_t)row * 16) * (1.0f / DM) + EPS);
; #pragma unroll
;                     for (int bj = 0; bj < 2; ++bj) {
;                         const f32x4 v0 = acc[ai][bj][m][0] * rs, v1 = acc[ai][bj][m][1] * rs;
;                         u32x4 w; w.x = cvtpk(v0[0], v0[1]); w.y = cvtpk(v0[2], v0[3]); w.z = cvtpk(v1[0], v1[1]); w.w = cvtpk(v1[2], v1[3]);
;                         *(u32x4*)(O + (size_t)row * 2048 + col0 + bj * HALF) = w;
;                     }
;                 }
	v_mul_f32_e32 v76, v145, v76
	v_mul_f32_e32 v77, v145, v77
	v_mul_f32_e32 v78, v145, v78
	v_mul_f32_e32 v79, v145, v79
	v_mul_f32_e32 v72, v145, v72
	v_mul_f32_e32 v73, v145, v73
	v_mul_f32_e32 v74, v145, v74
	v_mul_f32_e32 v75, v145, v75
	v_mul_f32_e32 v68, v145, v68
	v_mul_f32_e32 v69, v145, v69
	v_mul_f32_e32 v70, v145, v70
	v_mul_f32_e32 v71, v145, v71
	v_mul_f32_e32 v64, v145, v64
	v_mul_f32_e32 v65, v145, v65
	v_mul_f32_e32 v66, v145, v66
	v_mul_f32_e32 v67, v145, v67
	v_cvt_pk_bf16_f32 v76, v76, v77
	v_cvt_pk_bf16_f32 v77, v78, v79
	v_cvt_pk_bf16_f32 v78, v72, v73
	v_cvt_pk_bf16_f32 v79, v74, v75
	v_cvt_pk_bf16_f32 v68, v68, v69
	v_cvt_pk_bf16_f32 v69, v70, v71
	v_cvt_pk_bf16_f32 v70, v64, v65
	v_cvt_pk_bf16_f32 v71, v66, v67
	v_add_u32_e32 v141, 0x30000, v140
	global_store_dwordx4 v141, v[76:79], s[22:23]
	global_store_dwordx4 v141, v[68:71], s[22:23] offset:256
	s_waitcnt lgkmcnt(3)
	v_mul_f32_e32 v60, v146, v60
	v_mul_f32_e32 v61, v146, v61
	v_mul_f32_e32 v62, v146, v62
	v_mul_f32_e32 v63, v146, v63
	v_mul_f32_e32 v56, v146, v56
	v_mul_f32_e32 v57, v146, v57
	v_mul_f32_e32 v58, v146, v58
	v_mul_f32_e32 v59, v146, v59
	v_mul_f32_e32 v52, v146, v52
	v_mul_f32_e32 v53, v146, v53
	v_mul_f32_e32 v54, v146, v54
	v_mul_f32_e32 v55, v146, v55
	v_mul_f32_e32 v48, v146, v48
	v_mul_f32_e32 v49, v146, v49
	v_mul_f32_e32 v50, v146, v50
	v_mul_f32_e32 v51, v146, v51
	v_cvt_pk_bf16_f32 v60, v60, v61
	v_cvt_pk_bf16_f32 v61, v62, v63
	v_cvt_pk_bf16_f32 v62, v56, v57
	v_cvt_pk_bf16_f32 v63, v58, v59
	v_cvt_pk_bf16_f32 v52, v52, v53
	v_cvt_pk_bf16_f32 v53, v54, v55
	v_cvt_pk_bf16_f32 v54, v48, v49
	v_cvt_pk_bf16_f32 v55, v50, v51
	v_add_u32_e32 v141, 0x80000, v140
	global_store_dwordx4 v141, v[60:63], s[22:23]
	global_store_dwordx4 v141, v[52:55], s[22:23] offset:256
	s_waitcnt lgkmcnt(2)
	v_mul_f32_e32 v44, v147, v44
	v_mul_f32_e32 v45, v147, v45
	v_mul_f32_e32 v46, v147, v46
	v_mul_f32_e32 v47, v147, v47
	v_mul_f32_e32 v40, v147, v40
	v_mul_f32_e32 v41, v147, v41
	v_mul_f32_e32 v42, v147, v42
	v_mul_f32_e32 v43, v147, v43
	v_mul_f32_e32 v36, v147, v36
	v_mul_f32_e32 v37, v147, v37
	v_mul_f32_e32 v38, v147, v38
	v_mul_f32_e32 v39, v147, v39
	v_mul_f32_e32 v32, v147, v32
	v_mul_f32_e32 v33, v147, v33
	v_mul_f32_e32 v34, v147, v34
	v_mul_f32_e32 v35, v147, v35
	v_cvt_pk_bf16_f32 v44, v44, v45
	v_cvt_pk_bf16_f32 v45, v46, v47
	v_cvt_pk_bf16_f32 v46, v40, v41
	v_cvt_pk_bf16_f32 v47, v42, v43
	v_cvt_pk_bf16_f32 v36, v36, v37
	v_cvt_pk_bf16_f32 v37, v38, v39
	v_cvt_pk_bf16_f32 v38, v32, v33
	v_cvt_pk_bf16_f32 v39, v34, v35
	v_add_u32_e32 v141, 0x90000, v140
	global_store_dwordx4 v141, v[44:47], s[22:23]
	global_store_dwordx4 v141, v[36:39], s[22:23] offset:256
	s_waitcnt lgkmcnt(1)
	v_mul_f32_e32 v28, v148, v28
	v_mul_f32_e32 v29, v148, v29
	v_mul_f32_e32 v30, v148, v30
	v_mul_f32_e32 v31, v148, v31
	v_mul_f32_e32 v24, v148, v24
	v_mul_f32_e32 v25, v148, v25
	v_mul_f32_e32 v26, v148, v26
	v_mul_f32_e32 v27, v148, v27
	v_mul_f32_e32 v20, v148, v20
	v_mul_f32_e32 v21, v148, v21
	v_mul_f32_e32 v22, v148, v22
	v_mul_f32_e32 v23, v148, v23
	v_mul_f32_e32 v16, v148, v16
	v_mul_f32_e32 v17, v148, v17
	v_mul_f32_e32 v18, v148, v18
	v_mul_f32_e32 v19, v148, v19
	v_cvt_pk_bf16_f32 v28, v28, v29
	v_cvt_pk_bf16_f32 v29, v30, v31
	v_cvt_pk_bf16_f32 v30, v24, v25
	v_cvt_pk_bf16_f32 v31, v26, v27
	v_cvt_pk_bf16_f32 v20, v20, v21
	v_cvt_pk_bf16_f32 v21, v22, v23
	v_cvt_pk_bf16_f32 v22, v16, v17
	v_cvt_pk_bf16_f32 v23, v18, v19
	v_add_u32_e32 v141, 0xa0000, v140
	global_store_dwordx4 v141, v[28:31], s[22:23]
	global_store_dwordx4 v141, v[20:23], s[22:23] offset:256
	s_waitcnt lgkmcnt(0)
	v_mul_f32_e32 v12, v149, v12
	v_mul_f32_e32 v13, v149, v13
	v_mul_f32_e32 v14, v149, v14
	v_mul_f32_e32 v15, v149, v15
	v_mul_f32_e32 v8, v149, v8
	v_mul_f32_e32 v9, v149, v9
	v_mul_f32_e32 v10, v149, v10
	v_mul_f32_e32 v11, v149, v11
	v_mul_f32_e32 v4, v149, v4
	v_mul_f32_e32 v5, v149, v5
	v_mul_f32_e32 v6, v149, v6
	v_mul_f32_e32 v7, v149, v7
	v_mul_f32_e32 v0, v149, v0
	v_mul_f32_e32 v1, v149, v1
	v_mul_f32_e32 v2, v149, v2
	v_mul_f32_e32 v3, v149, v3
	v_cvt_pk_bf16_f32 v12, v12, v13
	v_cvt_pk_bf16_f32 v13, v14, v15
	v_cvt_pk_bf16_f32 v14, v8, v9
	v_cvt_pk_bf16_f32 v15, v10, v11
	v_cvt_pk_bf16_f32 v4, v4, v5
	v_cvt_pk_bf16_f32 v5, v6, v7
	v_cvt_pk_bf16_f32 v6, v0, v1
	v_cvt_pk_bf16_f32 v7, v2, v3
	v_add_u32_e32 v141, 0xb0000, v140
	global_store_dwordx4 v141, v[12:15], s[22:23]
	global_store_dwordx4 v141, v[4:7], s[22:23] offset:256
	s_andn2_b64 vcc, exec, s[6:7]
	s_mov_b64 s[6:7], -1
	s_cbranch_vccnz .LBB0_464
